# static s_setprio 1 for waves 4-7 during the phase-19 attention loops (strategy 4)
# speedup vs baseline: 1.0022x; 1.0022x over previous
; __global__ void __launch_bounds__(NTHREADS, 2) hybrid_fwd(Params P) {
;     ...
;         if (EN(11) && ph == 19) { ROOTS
;             const bf16_t* u = (const bf16_t*)(big + B1_U); const bf16_t* q = (const bf16_t*)(big + B1_Q); const bf16_t* kv = (const bf16_t*)(big + B1_KV); bf16_t* y = (bf16_t*)(big + B1_Y);
;             const int vb = (G & 7) == 0 ? ((bx & 7) * (G >> 3) + (bx >> 3)) : bx;
;             for (int un = vb; un < NB * 16 * 8; un += G) {
.LBB0_493:
	s_cmp_ge_u32 s1, 0x100
	s_cbranch_scc0 .Lprio19_skip
	s_setprio 1

; __global__ void __launch_bounds__(NTHREADS, 2) hybrid_fwd(Params P) {
;     ...
;         if (EN(7) && ph == 7) { ROOTS
;             const int nscan = G / 2;
;             if (EN(8) && bx < nscan) { for (int un = bx; un < NB * 16; un += nscan) rwkv_unit(lds, PL, un >> 4, un & 15, tid); }
;             else {
;                 const bf16_t* u = (const bf16_t*)(big + B0_U); bf16_t* y = (bf16_t*)(big + B0_Y);
;                 const int nsw = G - nscan; const int vsw = ((nsw & 7) == 0 && (nscan & 7) == 0) ? ((bx & 7) * (nsw >> 3) + ((bx - nscan) >> 3)) : (bx - nscan);
.LBB0_605:
	s_setprio 0
	s_and_b64 vcc, exec, s[18:19]
	s_cbranch_vccz .LBB0_774
	s_cmp_eq_u32 s58, 7
	s_cbranch_scc0 .LBB0_774
	v_mov_b32_e32 v1, v236
	s_mov_b32 s8, s56
	s_lshr_b32 s2, s8, 31
	s_add_i32 s2, s8, s2
	s_mov_b32 s48, s73
	s_ashr_i32 s49, s2, 1
	s_mov_b64 s[0:1], s[30:31]
	v_readfirstlane_b32 s9, v1
	s_cmp_ge_i32 s48, s49
	s_mov_b64 s[4:5], -1
	s_cbranch_scc0 .LBB0_735
	s_sub_i32 s22, s8, s49
	s_or_b32 s2, s22, s49
	s_and_b32 s2, s2, 7
	s_cmp_lg_u32 s2, 0
	s_cbranch_scc0 .LBB0_933
	s_sub_i32 s2, s48, s49
	s_cbranch_execnz .LBB0_611
